# HG_H3 MFMA blocks one to four all batched (counted lgkmcnt), combination of the earlier variants
# speedup vs baseline: 1.0026x; 1.0020x over previous
; #define LAS __attribute__((address_space(3)))
; __device__ __forceinline__ unsigned pk2(float lo, float hi) { f32x2c v = {lo, hi}; return __builtin_bit_cast(unsigned, __builtin_convertvector(v, bf16x2c)); }
; __device__ __forceinline__ void hgrn_h3(LAS unsigned char* lds8, const int e) {
;     ...
;         const int fr = lane & 15, fq = lane >> 4;
;         f32x4 acc[4];
; #pragma unroll
;         for (int I = 0; I < 4; ++I) acc[I] = (f32x4){0.f, 0.f, 0.f, 0.f};
; #pragma unroll
;         for (int ks = 0; ks < 4; ++ks) { const bf16x8 a = *(const LAS bf16x8*)(ST + (16 * wave + fr) * RS128 + 32 * ks + 8 * fq);
; #pragma unroll
;             for (int I = 0; I < 4; ++I) { const bf16x8 bb = *(const LAS bf16x8*)(Qb + (16 * I + fr) * RS128 + 32 * ks + 8 * fq);
;                 acc[I] = __builtin_amdgcn_mfma_f32_16x16x32_bf16(a, bb, acc[I], 0, 0, 0); } }
; #pragma unroll
;         for (int I = 0; I < 4; ++I) {
;             const int rb = 8 * I * (I + 1);
;             f32x4 P[4];
; #pragma unroll
;             for (int Jt = 0; Jt < 4; ++Jt) { P[Jt] = (f32x4){0.f, 0.f, 0.f, 0.f};
;                 if (Jt <= I) {
; #pragma unroll
;                     for (int ks = 0; ks < 4; ++ks) { const bf16x8 a = *(const LAS bf16x8*)(KT + (rb + 16 * Jt + fr) * RS128 + 32 * ks + 8 * fq);
;                         const bf16x8 bb = *(const LAS bf16x8*)(Qt + (16 * I + fr) * RS128 + 32 * ks + 8 * fq);
;                         P[Jt] = __builtin_amdgcn_mfma_f32_16x16x32_bf16(a, bb, P[Jt], 0, 0, 0); }
;                     if (Jt == I) {
; #pragma unroll
;                         for (int r = 0; r < 4; ++r) P[Jt][r] = (4 * fq + r <= fr) ? P[Jt][r] : 0.f; }
;                 } }
; #pragma unroll
;             for (int s = 0; s < 2; ++s) if (2 * s <= I) {
;                 u32x4 pw; pw.x = pk2(P[2 * s][0], P[2 * s][1]); pw.y = pk2(P[2 * s][2], P[2 * s][3]); pw.z = pk2(P[2 * s + 1][0], P[2 * s + 1][1]); pw.w = pk2(P[2 * s + 1][2], P[2 * s + 1][3]);
;                 const s16x4 v0 = *(const LAS s16x4*)(VT + (16 * wave + fr) * RS64 + 32 * s + 4 * fq), v1 = *(const LAS s16x4*)(VT + (16 * wave + fr) * RS64 + 32 * s + 16 + 4 * fq);
;                 const bf16x8 a = (bf16x8){v0[0], v0[1], v0[2], v0[3], v1[0], v1[1], v1[2], v1[3]};
;                 acc[I] = __builtin_amdgcn_mfma_f32_16x16x32_bf16(a, __builtin_bit_cast(bf16x8, pw), acc[I], 0, 0, 0); }
.LBB0_754:
	s_or_b64 exec, exec, s[30:31]
	s_waitcnt lgkmcnt(0)
	s_barrier
	ds_read_b128 v[4:7], v53
	ds_read_b128 v[8:11], v79 offset:17408
	ds_read_b128 v[12:15], v79 offset:21760
	ds_read_b128 v[16:19], v79 offset:26112
	ds_read_b128 v[20:23], v79 offset:30464
	ds_read_b128 v[192:195], v53 offset:64
	ds_read_b128 v[196:199], v79 offset:17472
	ds_read_b128 v[200:203], v79 offset:21824
	ds_read_b128 v[204:207], v79 offset:26176
	ds_read_b128 v[208:211], v79 offset:30528
	ds_read_b128 v[212:215], v53 offset:128
	ds_read_b128 v[216:219], v79 offset:17536
	ds_read_b128 v[220:223], v79 offset:21888
	ds_read_b128 v[224:227], v79 offset:26240
	ds_read_b128 v[228:231], v79 offset:30592
	s_waitcnt lgkmcnt(13)
	v_mfma_f32_16x16x32_bf16 v[8:11], v[4:7], v[8:11], 0
	s_add_i32 s66, s66, s46
	s_add_i32 s4, s4, s5
	s_add_i32 s28, s28, s34
	s_waitcnt lgkmcnt(12)
	v_mfma_f32_16x16x32_bf16 v[12:15], v[4:7], v[12:15], 0
	v_lshl_add_u64 v[32:33], v[32:33], 0, s[2:3]
	s_cmpk_lt_i32 s66, 0x400
	s_waitcnt lgkmcnt(11)
	v_mfma_f32_16x16x32_bf16 v[16:19], v[4:7], v[16:19], 0
	s_waitcnt lgkmcnt(10)
	v_mfma_f32_16x16x32_bf16 v[4:7], v[4:7], v[20:23], 0
	ds_read_b128 v[236:239], v53 offset:192
	ds_read_b128 v[240:243], v79 offset:17600
	ds_read_b128 v[244:247], v79 offset:21952
	s_waitcnt lgkmcnt(11)
	v_mfma_f32_16x16x32_bf16 v[8:11], v[192:195], v[196:199], v[8:11]
	s_waitcnt lgkmcnt(10)
	v_mfma_f32_16x16x32_bf16 v[12:15], v[192:195], v[200:203], v[12:15]
	s_waitcnt lgkmcnt(9)
	v_mfma_f32_16x16x32_bf16 v[16:19], v[192:195], v[204:207], v[16:19]
	s_waitcnt lgkmcnt(8)
	v_mfma_f32_16x16x32_bf16 v[4:7], v[192:195], v[208:211], v[4:7]
	s_waitcnt lgkmcnt(6)
	v_mfma_f32_16x16x32_bf16 v[8:11], v[212:215], v[216:219], v[8:11]
	s_waitcnt lgkmcnt(5)
	v_mfma_f32_16x16x32_bf16 v[12:15], v[212:215], v[220:223], v[12:15]
	s_waitcnt lgkmcnt(4)
	v_mfma_f32_16x16x32_bf16 v[16:19], v[212:215], v[224:227], v[16:19]
	s_waitcnt lgkmcnt(3)
	v_mfma_f32_16x16x32_bf16 v[4:7], v[212:215], v[228:231], v[4:7]
	s_waitcnt lgkmcnt(1)
	v_mfma_f32_16x16x32_bf16 v[8:11], v[236:239], v[240:243], v[8:11]
	s_waitcnt lgkmcnt(0)
	v_mfma_f32_16x16x32_bf16 v[82:85], v[236:239], v[244:247], v[12:15]
	s_nop 2
	ds_read_b128 v[12:15], v79 offset:26304
	s_waitcnt lgkmcnt(0)
	v_mfma_f32_16x16x32_bf16 v[20:23], v[236:239], v[12:15], v[16:19]
	ds_read_b128 v[12:15], v79 offset:30656
	s_waitcnt lgkmcnt(0)
	v_mfma_f32_16x16x32_bf16 v[4:7], v[236:239], v[12:15], v[4:7]
	ds_read_b128 v[12:15], v79 offset:34816
	ds_read_b128 v[16:19], v79
	ds_read_b128 v[192:195], v79 offset:34880
	ds_read_b128 v[24:27], v79 offset:64
	ds_read_b128 v[196:199], v79 offset:34944
	ds_read_b128 v[200:203], v79 offset:128
	ds_read_b128 v[204:207], v79 offset:35008
	ds_read_b128 v[208:211], v79 offset:192
	s_waitcnt lgkmcnt(6)
	v_mfma_f32_16x16x32_bf16 v[12:15], v[12:15], v[16:19], 0
	s_waitcnt lgkmcnt(4)
	v_mfma_f32_16x16x32_bf16 v[12:15], v[192:195], v[24:27], v[12:15]
	s_waitcnt lgkmcnt(2)
	v_mfma_f32_16x16x32_bf16 v[12:15], v[196:199], v[200:203], v[12:15]
	s_waitcnt lgkmcnt(0)
	v_mfma_f32_16x16x32_bf16 v[12:15], v[204:207], v[208:211], v[12:15]
	v_mov_b32_e32 v18, v3
	v_mov_b32_e32 v19, v3
	s_nop 5
	v_cndmask_b32_e64 v12, v12, 0, s[20:21]
	v_cndmask_b32_e64 v13, 0, v13, s[22:23]
	v_cndmask_b32_e64 v14, v14, 0, s[24:25]
	v_cndmask_b32_e64 v15, v15, 0, s[26:27]
	v_cvt_pk_bf16_f32 v16, v12, v13
	v_cvt_pk_bf16_f32 v17, v14, v15
	ds_read2_b64 v[12:15], v81 offset1:4
	s_waitcnt lgkmcnt(0)
	v_mfma_f32_16x16x32_bf16 v[8:11], v[12:15], v[16:19], v[8:11]
	ds_read_b128 v[16:19], v79 offset:39168
	ds_read_b128 v[24:27], v79 offset:4352
	ds_read_b128 v[86:89], v79 offset:39232
	ds_read_b128 v[90:93], v79 offset:4416
	ds_read_b128 v[192:195], v79 offset:39296
	ds_read_b128 v[94:97], v79 offset:4480
	ds_read_b128 v[196:199], v79 offset:39360
	ds_read_b128 v[98:101], v79 offset:4544
	ds_read_b128 v[200:203], v79 offset:43520
	ds_read_b128 v[204:207], v79 offset:43584
	ds_read_b128 v[208:211], v79 offset:43648
	ds_read_b128 v[212:215], v79 offset:43712
	s_waitcnt lgkmcnt(10)
	v_mfma_f32_16x16x32_bf16 v[16:19], v[16:19], v[24:27], 0
	s_waitcnt lgkmcnt(8)
	v_mfma_f32_16x16x32_bf16 v[16:19], v[86:89], v[90:93], v[16:19]
	s_waitcnt lgkmcnt(6)
	v_mfma_f32_16x16x32_bf16 v[16:19], v[192:195], v[94:97], v[16:19]
	s_waitcnt lgkmcnt(4)
	v_mfma_f32_16x16x32_bf16 v[16:19], v[196:199], v[98:101], v[16:19]
	s_waitcnt lgkmcnt(3)
	v_mfma_f32_16x16x32_bf16 v[24:27], v[200:203], v[24:27], 0
	s_nop 4
	v_cvt_pk_bf16_f32 v16, v16, v17
	v_cvt_pk_bf16_f32 v17, v18, v19
	s_waitcnt lgkmcnt(2)
	v_mfma_f32_16x16x32_bf16 v[24:27], v[204:207], v[90:93], v[24:27]
	s_waitcnt lgkmcnt(1)
	v_mfma_f32_16x16x32_bf16 v[24:27], v[208:211], v[94:97], v[24:27]
	s_waitcnt lgkmcnt(0)
	v_mfma_f32_16x16x32_bf16 v[24:27], v[212:215], v[98:101], v[24:27]
	s_nop 7
	v_cndmask_b32_e64 v24, v24, 0, s[20:21]
	v_cndmask_b32_e64 v25, 0, v25, s[22:23]
	v_cndmask_b32_e64 v26, v26, 0, s[24:25]
	v_cndmask_b32_e64 v27, v27, 0, s[26:27]
	v_cvt_pk_bf16_f32 v18, v24, v25
	v_cvt_pk_bf16_f32 v19, v26, v27
	s_nop 1
	v_mfma_f32_16x16x32_bf16 v[16:19], v[12:15], v[16:19], v[82:85]
	ds_read_b128 v[24:27], v79 offset:47872
	s_nop 1
	ds_read_b128 v[82:85], v79 offset:8704
	ds_read_b128 v[86:89], v79 offset:47936
	ds_read_b128 v[90:93], v79 offset:8768
	ds_read_b128 v[192:195], v79 offset:48000
	ds_read_b128 v[94:97], v79 offset:8832
	ds_read_b128 v[196:199], v79 offset:48064
	ds_read_b128 v[98:101], v79 offset:8896
	ds_read_b128 v[102:105], v79 offset:52288
	ds_read_b128 v[200:203], v79 offset:52224
	ds_read_b128 v[204:207], v79 offset:52352
	ds_read_b128 v[208:211], v79 offset:52416
	ds_read_b128 v[212:215], v79 offset:56576
	ds_read_b128 v[216:219], v79 offset:56640
	ds_read_b128 v[220:223], v79 offset:56704
	s_waitcnt lgkmcnt(13)
; #define LAS __attribute__((address_space(3)))
; __device__ __forceinline__ unsigned pk2(float lo, float hi) { f32x2c v = {lo, hi}; return __builtin_bit_cast(unsigned, __builtin_convertvector(v, bf16x2c)); }
; __device__ __forceinline__ void hgrn_h3(LAS unsigned char* lds8, const int e) {
;     ...
;         for (int I = 0; I < 4; ++I) {
;             const int rb = 8 * I * (I + 1);
;             f32x4 P[4];
; #pragma unroll
;             for (int Jt = 0; Jt < 4; ++Jt) { P[Jt] = (f32x4){0.f, 0.f, 0.f, 0.f};
;                 if (Jt <= I) {
; #pragma unroll
;                     for (int ks = 0; ks < 4; ++ks) { const bf16x8 a = *(const LAS bf16x8*)(KT + (rb + 16 * Jt + fr) * RS128 + 32 * ks + 8 * fq);
;                         const bf16x8 bb = *(const LAS bf16x8*)(Qt + (16 * I + fr) * RS128 + 32 * ks + 8 * fq);
;                         P[Jt] = __builtin_amdgcn_mfma_f32_16x16x32_bf16(a, bb, P[Jt], 0, 0, 0); }
;                     if (Jt == I) {
; #pragma unroll
;                         for (int r = 0; r < 4; ++r) P[Jt][r] = (4 * fq + r <= fr) ? P[Jt][r] : 0.f; }
;                 } }
; #pragma unroll
;             for (int s = 0; s < 2; ++s) if (2 * s <= I) {
;                 u32x4 pw; pw.x = pk2(P[2 * s][0], P[2 * s][1]); pw.y = pk2(P[2 * s][2], P[2 * s][3]); pw.z = pk2(P[2 * s + 1][0], P[2 * s + 1][1]); pw.w = pk2(P[2 * s + 1][2], P[2 * s + 1][3]);
;                 const s16x4 v0 = *(const LAS s16x4*)(VT + (16 * wave + fr) * RS64 + 32 * s + 4 * fq), v1 = *(const LAS s16x4*)(VT + (16 * wave + fr) * RS64 + 32 * s + 16 + 4 * fq);
;                 const bf16x8 a = (bf16x8){v0[0], v0[1], v0[2], v0[3], v1[0], v1[1], v1[2], v1[3]};
;                 acc[I] = __builtin_amdgcn_mfma_f32_16x16x32_bf16(a, __builtin_bit_cast(bf16x8, pw), acc[I], 0, 0, 0); }
;         }
; #pragma unroll
;         for (int I = 0; I < 4; ++I) *(f32x4*)(O0 + (size_t)(m0 + 16 * I + fr) * 1024 + h * 128 + 16 * wave + 4 * fq) = acc[I];
	v_mfma_f32_16x16x32_bf16 v[24:27], v[24:27], v[82:85], 0
	s_waitcnt lgkmcnt(11)
	v_mfma_f32_16x16x32_bf16 v[24:27], v[86:89], v[90:93], v[24:27]
	ds_read_b128 v[224:227], v79 offset:56768
	s_waitcnt lgkmcnt(10)
	v_mfma_f32_16x16x32_bf16 v[24:27], v[192:195], v[94:97], v[24:27]
	s_waitcnt lgkmcnt(8)
	v_mfma_f32_16x16x32_bf16 v[24:27], v[196:199], v[98:101], v[24:27]
	s_waitcnt lgkmcnt(6)
	v_mfma_f32_16x16x32_bf16 v[86:89], v[200:203], v[82:85], 0
	s_nop 5
	v_cvt_pk_bf16_f32 v24, v24, v25
	v_cvt_pk_bf16_f32 v25, v26, v27
	v_mfma_f32_16x16x32_bf16 v[86:89], v[102:105], v[90:93], v[86:89]
	s_waitcnt lgkmcnt(5)
	v_mfma_f32_16x16x32_bf16 v[86:89], v[204:207], v[94:97], v[86:89]
	s_waitcnt lgkmcnt(4)
	v_mfma_f32_16x16x32_bf16 v[86:89], v[208:211], v[98:101], v[86:89]
	s_nop 7
	v_cvt_pk_bf16_f32 v26, v86, v87
	s_waitcnt lgkmcnt(3)
	v_mfma_f32_16x16x32_bf16 v[82:85], v[212:215], v[82:85], 0
	v_cvt_pk_bf16_f32 v27, v88, v89
	s_waitcnt lgkmcnt(2)
	v_mfma_f32_16x16x32_bf16 v[82:85], v[216:219], v[90:93], v[82:85]
	s_waitcnt lgkmcnt(1)
	v_mfma_f32_16x16x32_bf16 v[82:85], v[220:223], v[94:97], v[82:85]
	v_mfma_f32_16x16x32_bf16 v[20:23], v[12:15], v[24:27], v[20:23]
	ds_read2_b64 v[24:27], v81 offset0:8 offset1:12
	s_waitcnt lgkmcnt(1)
	v_mfma_f32_16x16x32_bf16 v[82:85], v[224:227], v[98:101], v[82:85]
	s_nop 7
	v_cndmask_b32_e64 v82, v82, 0, s[20:21]
	v_cndmask_b32_e64 v83, 0, v83, s[22:23]
	v_cndmask_b32_e64 v84, v84, 0, s[24:25]
	v_cndmask_b32_e64 v85, v85, 0, s[26:27]
	v_cvt_pk_bf16_f32 v82, v82, v83
	v_cvt_pk_bf16_f32 v83, v84, v85
	v_mov_b32_e32 v84, v3
	v_mov_b32_e32 v85, v3
	s_waitcnt lgkmcnt(0)
	s_nop 0
	v_mfma_f32_16x16x32_bf16 v[20:23], v[24:27], v[82:85], v[20:23]
	ds_read_b128 v[82:85], v79 offset:60928
	ds_read_b128 v[86:89], v79 offset:13056
	ds_read_b128 v[90:93], v79 offset:60992
	ds_read_b128 v[94:97], v79 offset:13120
	s_waitcnt lgkmcnt(2)
	v_mfma_f32_16x16x32_bf16 v[82:85], v[82:85], v[86:89], 0
	s_waitcnt lgkmcnt(0)
	v_mfma_f32_16x16x32_bf16 v[82:85], v[90:93], v[94:97], v[82:85]
	ds_read_b128 v[90:93], v79 offset:61056
	ds_read_b128 v[98:101], v79 offset:13184
	s_waitcnt lgkmcnt(0)
	v_mfma_f32_16x16x32_bf16 v[82:85], v[90:93], v[98:101], v[82:85]
	ds_read_b128 v[90:93], v79 offset:61120
	ds_read_b128 v[102:105], v79 offset:13248
	ds_read_b128 v[106:109], v79 offset:65344
	ds_read_b128 v[110:113], v80 offset:34880
	s_waitcnt lgkmcnt(2)
	v_mfma_f32_16x16x32_bf16 v[82:85], v[90:93], v[102:105], v[82:85]
	ds_read_b128 v[90:93], v79 offset:65280
	s_waitcnt lgkmcnt(0)
	v_mfma_f32_16x16x32_bf16 v[90:93], v[90:93], v[86:89], 0
	s_nop 4
	v_cvt_pk_bf16_f32 v82, v82, v83
	v_cvt_pk_bf16_f32 v83, v84, v85
	v_mfma_f32_16x16x32_bf16 v[90:93], v[106:109], v[94:97], v[90:93]
	ds_read_b128 v[106:109], v79 offset:65408
	s_waitcnt lgkmcnt(0)
	v_mfma_f32_16x16x32_bf16 v[90:93], v[106:109], v[98:101], v[90:93]
	ds_read_b128 v[106:109], v79 offset:65472
	s_waitcnt lgkmcnt(0)
	v_mfma_f32_16x16x32_bf16 v[90:93], v[106:109], v[102:105], v[90:93]
	ds_read_b128 v[106:109], v80 offset:34816
	s_nop 6
	v_cvt_pk_bf16_f32 v84, v90, v91
	s_waitcnt lgkmcnt(0)
	v_mfma_f32_16x16x32_bf16 v[106:109], v[106:109], v[86:89], 0
	v_cvt_pk_bf16_f32 v85, v92, v93
	v_mfma_f32_16x16x32_bf16 v[106:109], v[110:113], v[94:97], v[106:109]
	ds_read_b128 v[110:113], v80 offset:34944
	s_waitcnt lgkmcnt(0)
	v_mfma_f32_16x16x32_bf16 v[106:109], v[110:113], v[98:101], v[106:109]
	ds_read_b128 v[110:113], v80 offset:35008
	s_waitcnt lgkmcnt(0)
	v_mfma_f32_16x16x32_bf16 v[106:109], v[110:113], v[102:105], v[106:109]
	ds_read_b128 v[110:113], v80 offset:39168
	s_waitcnt lgkmcnt(0)
	v_mfma_f32_16x16x32_bf16 v[86:89], v[110:113], v[86:89], 0
	ds_read_b128 v[110:113], v80 offset:39232
	s_waitcnt lgkmcnt(0)
	v_mfma_f32_16x16x32_bf16 v[86:89], v[110:113], v[94:97], v[86:89]
	ds_read_b128 v[94:97], v80 offset:39296
	s_waitcnt lgkmcnt(0)
	v_mfma_f32_16x16x32_bf16 v[86:89], v[94:97], v[98:101], v[86:89]
	ds_read_b128 v[94:97], v80 offset:39360
	s_waitcnt lgkmcnt(0)
	v_mfma_f32_16x16x32_bf16 v[86:89], v[94:97], v[102:105], v[86:89]
	s_nop 7
	v_cndmask_b32_e64 v86, v86, 0, s[20:21]
	v_mfma_f32_16x16x32_bf16 v[4:7], v[12:15], v[82:85], v[4:7]
	v_cndmask_b32_e64 v87, 0, v87, s[22:23]
	v_cndmask_b32_e64 v88, v88, 0, s[24:25]
	v_cndmask_b32_e64 v89, v89, 0, s[26:27]
	v_cvt_pk_bf16_f32 v12, v106, v107
	v_cvt_pk_bf16_f32 v13, v108, v109
	v_cvt_pk_bf16_f32 v14, v86, v87
	v_cvt_pk_bf16_f32 v15, v88, v89
	s_nop 1
	v_mfma_f32_16x16x32_bf16 v[4:7], v[24:27], v[12:15], v[4:7]
	v_or_b32_e32 v12, s35, v52
	v_ashrrev_i32_e32 v13, 31, v12
	v_lshl_add_u64 v[14:15], s[52:53], 2, v[28:29]
	v_lshlrev_b64 v[24:25], 12, v[12:13]
	v_lshl_add_u64 v[24:25], v[14:15], 0, v[24:25]
	global_store_dwordx4 v[24:25], v[8:11], off
	s_nop 1
	v_or_b32_e32 v8, 16, v12
	v_ashrrev_i32_e32 v9, 31, v8
	v_lshlrev_b64 v[8:9], 12, v[8:9]
	v_lshl_add_u64 v[8:9], v[14:15], 0, v[8:9]
	global_store_dwordx4 v[8:9], v[16:19], off
	v_or_b32_e32 v8, 32, v12
	v_ashrrev_i32_e32 v9, 31, v8
	v_lshlrev_b64 v[8:9], 12, v[8:9]
	v_lshl_add_u64 v[8:9], v[14:15], 0, v[8:9]
	global_store_dwordx4 v[8:9], v[20:23], off
	v_or_b32_e32 v8, 48, v12
	v_ashrrev_i32_e32 v9, 31, v8
	v_lshlrev_b64 v[8:9], 12, v[8:9]
	v_lshl_add_u64 v[8:9], v[14:15], 0, v[8:9]
	global_store_dwordx4 v[8:9], v[4:7], off
	s_cbranch_scc0 .LBB0_887
